# attention main loop: M0 save/restore dropped around the 6 LDS-DMA issues per iteration (nothing else in the kernel reads M0); on v105
# baseline (speedup 1.0000x reference)
; __device__ __forceinline__ void glds16(const void*gsrc,unsigned lds_dst){unsigned keep;
;   asm volatile("s_mov_b32 %0, m0\n\ts_mov_b32 m0, %2\n\ts_nop 0\n\tglobal_load_lds_dwordx4 %1, off\n\ts_mov_b32 m0, %0":"=&s"(keep):"v"(gsrc),"s"(lds_dst):"memory");}
.LBB0_369:
	s_lshl_b32 s20, s20, 1
	v_add_u32_e32 v187, s20, v224
	ds_read_b128 v[96:99], v222
	ds_read_b128 v[228:231], v222 offset:1024
	ds_read_b128 v[232:235], v222 offset:2048
	ds_read_b128 v[248:251], v222 offset:3072
	ds_read_b64_tr_b16 v[176:177], v187 offset:24576
	ds_read_b64_tr_b16 v[178:179], v187 offset:25088
	s_waitcnt lgkmcnt(5)
	v_mfma_f32_32x32x16_bf16 v[112:127], v[168:171], v[96:99], v[192:207]
	v_add_f32_e32 v100, v80, v81
	v_add_f32_e32 v100, v82, v100
	v_add_f32_e32 v100, v83, v100
	v_add_f32_e32 v100, v84, v100
	v_add_f32_e32 v100, v85, v100
	v_cvt_pk_bf16_f32 v140, v80, v81
	v_cvt_pk_bf16_f32 v141, v82, v83
	ds_read_b64_tr_b16 v[168:169], v187 offset:28672
	ds_read_b64_tr_b16 v[170:171], v187 offset:29184
	v_add_f32_e32 v80, v86, v100
	v_mfma_f32_32x32x16_bf16 v[96:111], v[160:163], v[96:99], v[192:207]
	v_add_f32_e32 v80, v87, v80
	v_add_f32_e32 v80, v88, v80
	v_add_f32_e32 v80, v89, v80
	v_cvt_pk_bf16_f32 v142, v84, v85
	v_cvt_pk_bf16_f32 v143, v86, v87
	ds_read_b64_tr_b16 v[84:85], v187 offset:32768
	ds_read_b64_tr_b16 v[86:87], v187 offset:33280
	s_waitcnt lgkmcnt(8)
	v_mfma_f32_32x32x16_bf16 v[112:127], v[172:175], v[228:231], v[112:127]
	v_add_f32_e32 v80, v90, v80
	v_add_f32_e32 v80, v91, v80
	v_add_f32_e32 v80, v92, v80
	v_add_f32_e32 v128, v93, v80
	v_cvt_pk_bf16_f32 v136, v88, v89
	v_cvt_pk_bf16_f32 v137, v90, v91
	ds_read_b64_tr_b16 v[80:81], v187 offset:36864
	ds_read_b64_tr_b16 v[82:83], v187 offset:37376
	v_mfma_f32_32x32x16_bf16 v[96:111], v[156:159], v[228:231], v[96:111]
	v_add_f32_e32 v88, v94, v128
	v_add_f32_e32 v88, v95, v88
	v_add_f32_e32 v88, v64, v88
	v_add_f32_e32 v88, v65, v88
	v_cvt_pk_bf16_f32 v138, v92, v93
	v_cvt_pk_bf16_f32 v139, v94, v95
	ds_read_b64_tr_b16 v[92:93], v187 offset:25600
	ds_read_b64_tr_b16 v[94:95], v187 offset:26112
	s_waitcnt lgkmcnt(11)
	v_mfma_f32_32x32x16_bf16 v[112:127], v[164:167], v[232:235], v[112:127]
	v_add_f32_e32 v88, v66, v88
	v_add_f32_e32 v88, v67, v88
	v_add_f32_e32 v88, v68, v88
	v_add_f32_e32 v128, v69, v88
	v_cvt_pk_bf16_f32 v132, v64, v65
	v_cvt_pk_bf16_f32 v133, v66, v67
	ds_read_b64_tr_b16 v[88:89], v187 offset:29696
	ds_read_b64_tr_b16 v[90:91], v187 offset:30208
	v_mfma_f32_32x32x16_bf16 v[96:111], v[148:151], v[232:235], v[96:111]
	v_add_f32_e32 v64, v70, v128
	v_add_f32_e32 v64, v71, v64
	v_add_f32_e32 v64, v72, v64
	v_add_f32_e32 v64, v73, v64
	v_cvt_pk_bf16_f32 v134, v68, v69
	v_cvt_pk_bf16_f32 v135, v70, v71
	ds_read_b64_tr_b16 v[68:69], v187 offset:33792
	ds_read_b64_tr_b16 v[70:71], v187 offset:34304
	s_waitcnt lgkmcnt(14)
	v_mfma_f32_32x32x16_bf16 v[112:127], v[152:155], v[248:251], v[112:127]
	v_add_f32_e32 v64, v74, v64
	v_add_f32_e32 v64, v75, v64
	v_add_f32_e32 v64, v76, v64
	v_add_f32_e32 v148, v77, v64
	v_cvt_pk_bf16_f32 v128, v72, v73
	v_cvt_pk_bf16_f32 v129, v74, v75
	ds_read_b64_tr_b16 v[64:65], v187 offset:37888
	ds_read_b64_tr_b16 v[66:67], v187 offset:38400
	v_mfma_f32_32x32x16_bf16 v[96:111], v[144:147], v[248:251], v[96:111]
	v_add_f32_e32 v72, v78, v148
	v_add_f32_e32 v72, v79, v72
	v_add_f32_e32 v74, 0, v72
	v_cvt_pk_bf16_f32 v130, v76, v77
	v_cvt_pk_bf16_f32 v131, v78, v79
	v_lshl_add_u64 v[72:73], v[184:185], 0, s[90:91]
	s_add_i32 s20, s29, s42
	s_mov_b32 m0, s20
	s_nop 0
	global_load_lds_dwordx4 v[72:73], off
	s_movk_i32 s20, 0xc000
	s_mov_b32 s21, -1
	v_lshl_add_u64 v[72:73], v[182:183], 0, s[20:21]
	s_lshl_b32 s20, s28, 1
	s_add_i32 s20, s20, s43
	s_mov_b32 m0, s20
	s_nop 0
	global_load_lds_dwordx4 v[72:73], off
	v_lshl_add_u64 v[72:73], v[182:183], 0, s[90:91]
	s_addk_i32 s20, 0x2000
	s_mov_b32 m0, s20
	s_nop 0
	global_load_lds_dwordx4 v[72:73], off
	v_max_f32_e32 v72, v113, v113
	v_max_f32_e32 v73, v112, v112
	v_max_f32_e32 v72, v73, v72
	v_max3_f32 v73, v114, v115, v97
	v_max3_f32 v72, v72, v96, v98
	v_max3_f32 v72, v72, v99, v116
	v_max3_f32 v73, v73, v118, v119
	v_max3_f32 v72, v72, v117, v100
	v_max3_f32 v73, v73, v102, v103
	v_max3_f32 v72, v72, v101, v120
	v_max3_f32 v73, v73, v122, v123
	v_max3_f32 v72, v72, v121, v104
	v_max3_f32 v73, v73, v106, v107
	v_max3_f32 v72, v72, v105, v124
	v_max3_f32 v73, v73, v126, v127
	v_max3_f32 v72, v72, v125, v108
	v_max3_f32 v73, v73, v110, v111
	v_max3_f32 v72, v72, v109, v73
	v_mov_b32_e32 v73, v72
	s_nop 1
	v_permlane32_swap_b32_e32 v72, v73
	v_max_f32_e32 v73, v73, v73
	v_max_f32_e32 v72, v72, v72
	v_max_f32_e32 v72, v72, v73
	v_cmp_lt_f32_e32 vcc, s92, v72
	s_cmp_lg_u64 vcc, 0
	v_add_f32_e32 v190, v226, v74
	s_cselect_b64 s[20:21], -1, 0
	s_cbranch_vccnz .LBB0_377

; __device__ __forceinline__ void glds16(const void*gsrc,unsigned lds_dst){unsigned keep;
;   asm volatile("s_mov_b32 %0, m0\n\ts_mov_b32 m0, %2\n\ts_nop 0\n\tglobal_load_lds_dwordx4 %1, off\n\ts_mov_b32 m0, %0":"=&s"(keep):"v"(gsrc),"s"(lds_dst):"memory");}
.LBB0_372:
	s_add_i32 s20, s28, 0x2000
	s_cmpk_lg_i32 s28, 0x4000
	s_cselect_b32 s97, s20, 0
	s_lshl_b32 s20, s29, 1
	v_add_u32_e32 v191, s20, v224
	ds_read_b128 v[72:75], v222
	ds_read_b128 v[226:229], v222 offset:1024
	ds_read_b128 v[230:233], v222 offset:2048
	ds_read_b128 v[234:237], v222 offset:3072
	ds_read_b64_tr_b16 v[176:177], v191 offset:24576
	ds_read_b64_tr_b16 v[178:179], v191 offset:25088
	s_waitcnt lgkmcnt(5)
	v_mfma_f32_32x32x16_bf16 v[80:95], v[68:71], v[72:75], v[192:207]
	v_add_f32_e32 v76, v112, v113
	v_add_f32_e32 v76, v114, v76
	v_add_f32_e32 v76, v115, v76
	v_add_f32_e32 v76, v116, v76
	v_add_f32_e32 v76, v117, v76
	v_cvt_pk_bf16_f32 v140, v112, v113
	v_cvt_pk_bf16_f32 v141, v114, v115
	ds_read_b64_tr_b16 v[172:173], v191 offset:28672
	ds_read_b64_tr_b16 v[174:175], v191 offset:29184
	v_add_f32_e32 v68, v118, v76
	v_add_f32_e32 v68, v119, v68
	v_add_f32_e32 v68, v120, v68
	v_add_f32_e32 v112, v121, v68
	v_mfma_f32_32x32x16_bf16 v[64:79], v[64:67], v[72:75], v[192:207]
	v_cvt_pk_bf16_f32 v142, v116, v117
	v_cvt_pk_bf16_f32 v143, v118, v119
	ds_read_b64_tr_b16 v[168:169], v191 offset:32768
	ds_read_b64_tr_b16 v[170:171], v191 offset:33280
	s_waitcnt lgkmcnt(8)
	v_mfma_f32_32x32x16_bf16 v[80:95], v[164:167], v[226:229], v[80:95]
	v_add_f32_e32 v112, v122, v112
	v_add_f32_e32 v112, v123, v112
	v_add_f32_e32 v112, v124, v112
	v_add_f32_e32 v112, v125, v112
	v_cvt_pk_bf16_f32 v136, v120, v121
	v_cvt_pk_bf16_f32 v137, v122, v123
	ds_read_b64_tr_b16 v[120:121], v191 offset:36864
	ds_read_b64_tr_b16 v[122:123], v191 offset:37376
	v_mfma_f32_32x32x16_bf16 v[64:79], v[152:155], v[226:229], v[64:79]
	v_add_f32_e32 v112, v126, v112
	v_add_f32_e32 v112, v127, v112
	v_add_f32_e32 v112, v96, v112
	v_add_f32_e32 v112, v97, v112
	v_cvt_pk_bf16_f32 v138, v124, v125
	v_cvt_pk_bf16_f32 v139, v126, v127
	ds_read_b64_tr_b16 v[116:117], v191 offset:25600
	ds_read_b64_tr_b16 v[118:119], v191 offset:26112
	s_waitcnt lgkmcnt(11)
	v_mfma_f32_32x32x16_bf16 v[80:95], v[160:163], v[230:233], v[80:95]
	v_add_f32_e32 v112, v98, v112
	v_add_f32_e32 v112, v99, v112
	v_add_f32_e32 v112, v100, v112
	v_add_f32_e32 v124, v101, v112
	v_cvt_pk_bf16_f32 v132, v96, v97
	v_cvt_pk_bf16_f32 v133, v98, v99
	ds_read_b64_tr_b16 v[112:113], v191 offset:29696
	ds_read_b64_tr_b16 v[114:115], v191 offset:30208
	v_mfma_f32_32x32x16_bf16 v[64:79], v[148:151], v[230:233], v[64:79]
	v_add_f32_e32 v96, v102, v124
	v_add_f32_e32 v96, v103, v96
	v_add_f32_e32 v96, v104, v96
	v_add_f32_e32 v96, v105, v96
	v_cvt_pk_bf16_f32 v134, v100, v101
	v_cvt_pk_bf16_f32 v135, v102, v103
	ds_read_b64_tr_b16 v[100:101], v191 offset:33792
	ds_read_b64_tr_b16 v[102:103], v191 offset:34304
	s_waitcnt lgkmcnt(14)
	v_mfma_f32_32x32x16_bf16 v[80:95], v[156:159], v[234:237], v[80:95]
	v_add_f32_e32 v96, v106, v96
	v_add_f32_e32 v96, v107, v96
	v_add_f32_e32 v96, v108, v96
	v_add_f32_e32 v124, v109, v96
	v_cvt_pk_bf16_f32 v128, v104, v105
	v_cvt_pk_bf16_f32 v129, v106, v107
	ds_read_b64_tr_b16 v[96:97], v191 offset:37888
	ds_read_b64_tr_b16 v[98:99], v191 offset:38400
	v_mfma_f32_32x32x16_bf16 v[64:79], v[144:147], v[234:237], v[64:79]
	v_add_f32_e32 v104, v110, v124
	v_add_f32_e32 v104, v111, v104
	v_add_f32_e32 v106, 0, v104
	v_cvt_pk_bf16_f32 v130, v108, v109
	v_cvt_pk_bf16_f32 v131, v110, v111
	s_add_i32 s20, s28, s42
	s_mov_b32 m0, s20
	s_nop 0
	global_load_lds_dwordx4 v[184:185], off
	s_lshl_b32 s20, s97, 1
	s_add_i32 s20, s20, s43
	s_mov_b32 m0, s20
	s_nop 0
	global_load_lds_dwordx4 v[182:183], off
	v_lshl_add_u64 v[104:105], v[182:183], 0, s[84:85]
	s_addk_i32 s20, 0x2000
	s_mov_b32 m0, s20
	s_nop 0
	global_load_lds_dwordx4 v[104:105], off
	v_max_f32_e32 v104, v81, v81
	v_max_f32_e32 v105, v80, v80
	v_max_f32_e32 v104, v105, v104
	v_max3_f32 v105, v82, v83, v65
	v_max3_f32 v104, v104, v64, v66
	v_max3_f32 v104, v104, v67, v84
	v_max3_f32 v105, v105, v86, v87
	v_max3_f32 v104, v104, v85, v68
	v_max3_f32 v105, v105, v70, v71
	v_max3_f32 v104, v104, v69, v88
	v_max3_f32 v105, v105, v90, v91
	v_max3_f32 v104, v104, v89, v72
	v_max3_f32 v105, v105, v74, v75
	v_max3_f32 v104, v104, v73, v92
	v_max3_f32 v105, v105, v94, v95
	v_max3_f32 v104, v104, v93, v76
	v_max3_f32 v105, v105, v78, v79
	v_max3_f32 v104, v104, v77, v105
	v_mov_b32_e32 v105, v104
	s_nop 1
	v_permlane32_swap_b32_e32 v104, v105
	v_max_f32_e32 v105, v105, v105
	v_max_f32_e32 v104, v104, v104
	v_max_f32_e32 v104, v104, v105
	v_cmp_lt_f32_e32 vcc, s92, v104
	s_cmp_lg_u64 vcc, 0
	v_add_f32_e32 v226, v190, v106
	s_cselect_b64 s[20:21], -1, 0
	s_cbranch_vccnz .LBB0_380
